# RWKV-layer wo GEMM: bf16 residual added into the f32 accumulators during the K loop (two requests per pass, one pass ahead); epilogue only converts and stores
# speedup vs baseline: 1.0041x; 1.0041x over previous
; __device__ __forceinline__ u32x4 pack8(const f32x4 a, const f32x4 b) { u32x4 w; w.x = cvt_pk_bf16(a[0], a[1]); w.y = cvt_pk_bf16(a[2], a[3]); w.z = cvt_pk_bf16(b[0], b[1]); w.w = cvt_pk_bf16(b[2], b[3]); return w; }
; __device__ __forceinline__ void unpack8(const u32x4 w, f32x4& a, f32x4& b) { a = (f32x4){bflo(w.x), bfhi(w.x), bflo(w.y), bfhi(w.y)}; b = (f32x4){bflo(w.z), bfhi(w.z), bflo(w.w), bfhi(w.w)}; }
;     __device__ __forceinline__ void operator()(const f32x4 (&acc)[2][2][4][2], const Unit& u, int wr, int wc, int fr, int fq) const {
;     ...
;             for (int m = 0; m < 4; ++m) { const size_t off = (size_t)(row0 + ai * HALF + m * 16) * 1024 + col0;
; #pragma unroll
;                 for (int bj = 0; bj < 2; ++bj) { f32x4 b0, b1;
;                     if (BF) { unpack8(*(const u32x4*)((const bf16_t*)base + off + bj * HALF), b0, b1); }
;                     else { b0 = *(const f32x4*)((const float*)base + off + bj * HALF); b1 = *(const f32x4*)((const float*)base + off + bj * HALF + 4); }
;                     *(u32x4*)(O + off + bj * HALF) = pack8(b0 + acc[ai][bj][m][0], b1 + acc[ai][bj][m][1]); } }
; template <class Epi, class Sched, bool ALIGN_EPI = false, bool SP2 = false>
; __device__ __forceinline__ void gemm_phase(PG8_LAS unsigned char* lds, const Gemm g, const Sched& S, const Epi& E, const int tid_in) {
;     ...
; #pragma unroll
;         for (int a = 0; a < 2; ++a)
; #pragma unroll
;             for (int b = 0; b < 2; ++b)
; #pragma unroll
;                 for (int m = 0; m < 4; ++m)
; #pragma unroll
;                     for (int n = 0; n < 2; ++n) acc[a][b][m][n] = (f32x4){0.f, 0.f, 0.f, 0.f};
;         cur = nxt; cA = nA; cB = nB; ++ui;
.LBB0_1079:
	s_ashr_i32 s35, s34, 31
	s_lshl_b64 s[36:37], s[34:35], 19
	s_add_u32 s36, s48, s36
	s_addc_u32 s37, s49, s37
	s_and_b64 s[38:39], s[2:3], exec
	s_cselect_b32 s35, s37, s1
	s_cselect_b32 s66, s36, s0
	s_ashr_i32 s31, s30, 31
	s_lshl_b64 s[38:39], s[30:31], 19
	s_add_u32 s38, s52, s38
	s_addc_u32 s39, s53, s39
	s_and_b64 s[44:45], s[2:3], exec
	s_cselect_b32 s31, s39, s43
	s_cselect_b32 s67, s38, s42
	s_add_u32 s0, s0, 0x40080
	s_addc_u32 s1, s1, 0
	s_add_u32 s68, s42, 0x100
	v_mov_b32_e32 v0, 0
	s_addc_u32 s69, s43, 0
	s_mov_b32 s70, -2
	v_mov_b32_e32 v1, v0
	v_mov_b32_e32 v2, v0
	v_mov_b32_e32 v3, v0
	v_mov_b32_e32 v4, v0
	v_mov_b32_e32 v5, v0
	v_mov_b32_e32 v6, v0
	v_mov_b32_e32 v7, v0
	v_mov_b32_e32 v12, v0
	v_mov_b32_e32 v13, v0
	v_mov_b32_e32 v14, v0
	v_mov_b32_e32 v15, v0
	v_mov_b32_e32 v16, v0
	v_mov_b32_e32 v17, v0
	v_mov_b32_e32 v18, v0
	v_mov_b32_e32 v19, v0
	v_mov_b32_e32 v28, v0
	v_mov_b32_e32 v29, v0
	v_mov_b32_e32 v30, v0
	v_mov_b32_e32 v31, v0
	v_mov_b32_e32 v32, v0
	v_mov_b32_e32 v33, v0
	v_mov_b32_e32 v34, v0
	v_mov_b32_e32 v35, v0
	v_mov_b32_e32 v44, v0
	v_mov_b32_e32 v45, v0
	v_mov_b32_e32 v46, v0
	v_mov_b32_e32 v47, v0
	v_mov_b32_e32 v48, v0
	v_mov_b32_e32 v49, v0
	v_mov_b32_e32 v50, v0
	v_mov_b32_e32 v51, v0
	v_mov_b32_e32 v8, v0
	v_mov_b32_e32 v9, v0
	v_mov_b32_e32 v10, v0
	v_mov_b32_e32 v11, v0
	v_mov_b32_e32 v20, v0
	v_mov_b32_e32 v21, v0
	v_mov_b32_e32 v22, v0
	v_mov_b32_e32 v23, v0
	v_mov_b32_e32 v24, v0
	v_mov_b32_e32 v25, v0
	v_mov_b32_e32 v26, v0
	v_mov_b32_e32 v27, v0
	v_mov_b32_e32 v36, v0
	v_mov_b32_e32 v37, v0
	v_mov_b32_e32 v38, v0
	v_mov_b32_e32 v39, v0
	v_mov_b32_e32 v40, v0
	v_mov_b32_e32 v41, v0
	v_mov_b32_e32 v42, v0
	v_mov_b32_e32 v43, v0
	v_mov_b32_e32 v52, v0
	v_mov_b32_e32 v53, v0
	v_mov_b32_e32 v54, v0
	v_mov_b32_e32 v55, v0
	v_mov_b32_e32 v56, v0
	v_mov_b32_e32 v57, v0
	v_mov_b32_e32 v58, v0
	v_mov_b32_e32 v59, v0
	v_mov_b32_e32 v60, v0
	v_mov_b32_e32 v61, v0
	v_mov_b32_e32 v62, v0
	v_mov_b32_e32 v63, v0
	v_mov_b32_e32 v64, v0
	v_mov_b32_e32 v65, v0
	v_mov_b32_e32 v66, v0
	v_mov_b32_e32 v67, v0
	v_mov_b32_e32 v68, v0
	v_mov_b32_e32 v69, v0
	v_mov_b32_e32 v70, v0
	v_mov_b32_e32 v71, v0
	v_mov_b32_e32 v76, v0
	v_mov_b32_e32 v77, v0
	v_mov_b32_e32 v78, v0
	v_mov_b32_e32 v79, v0
	v_mov_b32_e32 v80, v0
	v_mov_b32_e32 v81, v0
	v_mov_b32_e32 v82, v0
	v_mov_b32_e32 v83, v0
	v_mov_b32_e32 v92, v0
	v_mov_b32_e32 v93, v0
	v_mov_b32_e32 v94, v0
	v_mov_b32_e32 v95, v0
	v_mov_b32_e32 v96, v0
	v_mov_b32_e32 v97, v0
	v_mov_b32_e32 v98, v0
	v_mov_b32_e32 v99, v0
	v_mov_b32_e32 v108, v0
	v_mov_b32_e32 v109, v0
	v_mov_b32_e32 v110, v0
	v_mov_b32_e32 v111, v0
	v_mov_b32_e32 v112, v0
	v_mov_b32_e32 v113, v0
	v_mov_b32_e32 v114, v0
	v_mov_b32_e32 v115, v0
	v_mov_b32_e32 v72, v0
	v_mov_b32_e32 v73, v0
	v_mov_b32_e32 v74, v0
	v_mov_b32_e32 v75, v0
	v_mov_b32_e32 v84, v0
	v_mov_b32_e32 v85, v0
	v_mov_b32_e32 v86, v0
	v_mov_b32_e32 v87, v0
	v_mov_b32_e32 v88, v0
	v_mov_b32_e32 v89, v0
	v_mov_b32_e32 v90, v0
	v_mov_b32_e32 v91, v0
	v_mov_b32_e32 v100, v0
	v_mov_b32_e32 v101, v0
	v_mov_b32_e32 v102, v0
	v_mov_b32_e32 v103, v0
	v_mov_b32_e32 v104, v0
	v_mov_b32_e32 v105, v0
	v_mov_b32_e32 v106, v0
	v_mov_b32_e32 v107, v0
	v_mov_b32_e32 v116, v0
	v_mov_b32_e32 v117, v0
	v_mov_b32_e32 v118, v0
	v_mov_b32_e32 v119, v0
	v_mov_b32_e32 v120, v0
	v_mov_b32_e32 v121, v0
	v_mov_b32_e32 v122, v0
	v_mov_b32_e32 v123, v0
	v_mov_b32_e32 v124, v0
	v_mov_b32_e32 v125, v0
	v_mov_b32_e32 v126, v0
	v_mov_b32_e32 v127, v0
	v_lshl_add_u32 v240, s40, 8, v165
	v_lshl_or_b32 v242, s65, 8, v167
	v_ashrrev_i32_e32 v241, 31, v240
	v_ashrrev_i32_e32 v243, 31, v242
	v_lshlrev_b64 v[240:241], 10, v[240:241]
	v_lshl_add_u64 v[240:241], v[240:241], 0, v[242:243]
	v_lshlrev_b64 v[240:241], 1, v[240:241]
	v_lshl_add_u64 v[240:241], s[16:17], 0, v[240:241]
.LBB0_1080:
	ds_read_b128 v[144:147], v168
	ds_read_b128 v[172:175], v168 offset:1024
	ds_read_b128 v[176:179], v168 offset:2048
	ds_read_b128 v[180:183], v168 offset:3072
	ds_read_b128 v[184:187], v169
	ds_read_b128 v[188:191], v169 offset:1024
	ds_read_b128 v[192:195], v169 offset:2048
	ds_read_b128 v[196:199], v169 offset:3072
	s_add_u32 s42, s0, 0xfffc0080
	s_addc_u32 s43, s1, -1
	s_cmp_eq_u32 s70, 12
	s_cselect_b32 s45, s35, s43
	s_cselect_b32 s44, s66, s42
	s_cselect_b32 s43, s31, s69
	s_cselect_b32 s42, s67, s68
	v_lshl_add_u64 v[148:149], s[0:1], 0, v[136:137]
	s_add_i32 m0, s41, 0xc000
	ds_read_b128 v[200:203], v170
	ds_read_b128 v[204:207], v170 offset:1024
	ds_read_b128 v[208:211], v170 offset:2048
	ds_read_b128 v[212:215], v170 offset:3072
	ds_read_b128 v[216:219], v170 offset:4096
	ds_read_b128 v[220:223], v170 offset:5120
	ds_read_b128 v[224:227], v170 offset:6144
	ds_read_b128 v[228:231], v170 offset:7168
	global_load_lds_dwordx4 v[148:149], off
	v_lshl_add_u64 v[148:149], s[0:1], 0, v[138:139]
	s_add_i32 m0, s41, 0xe000
	s_nop 0
	global_load_lds_dwordx4 v[148:149], off
	s_waitcnt vmcnt(8)
	s_waitcnt lgkmcnt(0)
	s_cmp_lt_i32 s70, 0
	s_cbranch_scc1 .Lmy_rb_done
	s_cmp_eq_u32 s70, 2
	s_cbranch_scc1 .Lmy_rb_1
	s_cmp_eq_u32 s70, 4
	s_cbranch_scc1 .Lmy_rb_2
	s_cmp_eq_u32 s70, 6
	s_cbranch_scc1 .Lmy_rb_3
	s_cmp_eq_u32 s70, 8
	s_cbranch_scc1 .Lmy_rb_4
	s_cmp_eq_u32 s70, 10
	s_cbranch_scc1 .Lmy_rb_5
	s_cmp_eq_u32 s70, 12
	s_cbranch_scc1 .Lmy_rb_6
	v_lshlrev_b32_e32 v250, 16, v242
	v_and_b32_e32 v242, 0xffff0000, v242
	v_add_f32_e32 v124, v124, v250
	v_add_f32_e32 v125, v125, v242
	v_lshlrev_b32_e32 v250, 16, v243
	v_and_b32_e32 v243, 0xffff0000, v243
	v_add_f32_e32 v126, v126, v250
	v_add_f32_e32 v127, v127, v243
	v_lshlrev_b32_e32 v250, 16, v244
	v_and_b32_e32 v244, 0xffff0000, v244
	v_add_f32_e32 v120, v120, v250
	v_add_f32_e32 v121, v121, v244
	v_lshlrev_b32_e32 v250, 16, v245
	v_and_b32_e32 v245, 0xffff0000, v245
	v_add_f32_e32 v122, v122, v250
	v_add_f32_e32 v123, v123, v245
	v_lshlrev_b32_e32 v250, 16, v246
	v_and_b32_e32 v246, 0xffff0000, v246
	v_add_f32_e32 v112, v112, v250
	v_add_f32_e32 v113, v113, v246
	v_lshlrev_b32_e32 v250, 16, v247
	v_and_b32_e32 v247, 0xffff0000, v247
	v_add_f32_e32 v114, v114, v250
	v_add_f32_e32 v115, v115, v247
	v_lshlrev_b32_e32 v250, 16, v248
	v_and_b32_e32 v248, 0xffff0000, v248
	v_add_f32_e32 v108, v108, v250
	v_add_f32_e32 v109, v109, v248
	v_lshlrev_b32_e32 v250, 16, v249
	v_and_b32_e32 v249, 0xffff0000, v249
	v_add_f32_e32 v110, v110, v250
	v_add_f32_e32 v111, v111, v249
	s_branch .Lmy_rb_done
; __device__ __forceinline__ u32x4 pack8(const f32x4 a, const f32x4 b) { u32x4 w; w.x = cvt_pk_bf16(a[0], a[1]); w.y = cvt_pk_bf16(a[2], a[3]); w.z = cvt_pk_bf16(b[0], b[1]); w.w = cvt_pk_bf16(b[2], b[3]); return w; }
; __device__ __forceinline__ void unpack8(const u32x4 w, f32x4& a, f32x4& b) { a = (f32x4){bflo(w.x), bfhi(w.x), bflo(w.y), bfhi(w.y)}; b = (f32x4){bflo(w.z), bfhi(w.z), bflo(w.w), bfhi(w.w)}; }
;     __device__ __forceinline__ void operator()(const f32x4 (&acc)[2][2][4][2], const Unit& u, int wr, int wc, int fr, int fq) const {
;     ...
;             for (int m = 0; m < 4; ++m) { const size_t off = (size_t)(row0 + ai * HALF + m * 16) * 1024 + col0;
; #pragma unroll
;                 for (int bj = 0; bj < 2; ++bj) { f32x4 b0, b1;
;                     if (BF) { unpack8(*(const u32x4*)((const bf16_t*)base + off + bj * HALF), b0, b1); }
;                     else { b0 = *(const f32x4*)((const float*)base + off + bj * HALF); b1 = *(const f32x4*)((const float*)base + off + bj * HALF + 4); }
;                     *(u32x4*)(O + off + bj * HALF) = pack8(b0 + acc[ai][bj][m][0], b1 + acc[ai][bj][m][1]); } }
.Lmy_rb_1:
	v_lshlrev_b32_e32 v250, 16, v242
	v_and_b32_e32 v242, 0xffff0000, v242
	v_add_f32_e32 v116, v116, v250
	v_add_f32_e32 v117, v117, v242
	v_lshlrev_b32_e32 v250, 16, v243
	v_and_b32_e32 v243, 0xffff0000, v243
	v_add_f32_e32 v118, v118, v250
	v_add_f32_e32 v119, v119, v243
	v_lshlrev_b32_e32 v250, 16, v244
	v_and_b32_e32 v244, 0xffff0000, v244
	v_add_f32_e32 v104, v104, v250
	v_add_f32_e32 v105, v105, v244
	v_lshlrev_b32_e32 v250, 16, v245
	v_and_b32_e32 v245, 0xffff0000, v245
	v_add_f32_e32 v106, v106, v250
	v_add_f32_e32 v107, v107, v245
	v_lshlrev_b32_e32 v250, 16, v246
	v_and_b32_e32 v246, 0xffff0000, v246
	v_add_f32_e32 v96, v96, v250
	v_add_f32_e32 v97, v97, v246
	v_lshlrev_b32_e32 v250, 16, v247
	v_and_b32_e32 v247, 0xffff0000, v247
	v_add_f32_e32 v98, v98, v250
	v_add_f32_e32 v99, v99, v247
	v_lshlrev_b32_e32 v250, 16, v248
	v_and_b32_e32 v248, 0xffff0000, v248
	v_add_f32_e32 v92, v92, v250
	v_add_f32_e32 v93, v93, v248
	v_lshlrev_b32_e32 v250, 16, v249
	v_and_b32_e32 v249, 0xffff0000, v249
	v_add_f32_e32 v94, v94, v250
	v_add_f32_e32 v95, v95, v249
	s_branch .Lmy_rb_done
.Lmy_rb_2:
	v_lshlrev_b32_e32 v250, 16, v242
	v_and_b32_e32 v242, 0xffff0000, v242
	v_add_f32_e32 v100, v100, v250
	v_add_f32_e32 v101, v101, v242
	v_lshlrev_b32_e32 v250, 16, v243
	v_and_b32_e32 v243, 0xffff0000, v243
	v_add_f32_e32 v102, v102, v250
	v_add_f32_e32 v103, v103, v243
	v_lshlrev_b32_e32 v250, 16, v244
	v_and_b32_e32 v244, 0xffff0000, v244
	v_add_f32_e32 v88, v88, v250
	v_add_f32_e32 v89, v89, v244
	v_lshlrev_b32_e32 v250, 16, v245
	v_and_b32_e32 v245, 0xffff0000, v245
	v_add_f32_e32 v90, v90, v250
	v_add_f32_e32 v91, v91, v245
	v_lshlrev_b32_e32 v250, 16, v246
	v_and_b32_e32 v246, 0xffff0000, v246
	v_add_f32_e32 v80, v80, v250
	v_add_f32_e32 v81, v81, v246
	v_lshlrev_b32_e32 v250, 16, v247
	v_and_b32_e32 v247, 0xffff0000, v247
	v_add_f32_e32 v82, v82, v250
	v_add_f32_e32 v83, v83, v247
	v_lshlrev_b32_e32 v250, 16, v248
	v_and_b32_e32 v248, 0xffff0000, v248
	v_add_f32_e32 v76, v76, v250
	v_add_f32_e32 v77, v77, v248
	v_lshlrev_b32_e32 v250, 16, v249
	v_and_b32_e32 v249, 0xffff0000, v249
	v_add_f32_e32 v78, v78, v250
	v_add_f32_e32 v79, v79, v249
	s_branch .Lmy_rb_done
.Lmy_rb_3:
	v_lshlrev_b32_e32 v250, 16, v242
	v_and_b32_e32 v242, 0xffff0000, v242
	v_add_f32_e32 v84, v84, v250
	v_add_f32_e32 v85, v85, v242
	v_lshlrev_b32_e32 v250, 16, v243
	v_and_b32_e32 v243, 0xffff0000, v243
	v_add_f32_e32 v86, v86, v250
	v_add_f32_e32 v87, v87, v243
	v_lshlrev_b32_e32 v250, 16, v244
	v_and_b32_e32 v244, 0xffff0000, v244
	v_add_f32_e32 v72, v72, v250
	v_add_f32_e32 v73, v73, v244
	v_lshlrev_b32_e32 v250, 16, v245
	v_and_b32_e32 v245, 0xffff0000, v245
	v_add_f32_e32 v74, v74, v250
	v_add_f32_e32 v75, v75, v245
	v_lshlrev_b32_e32 v250, 16, v246
	v_and_b32_e32 v246, 0xffff0000, v246
	v_add_f32_e32 v68, v68, v250
	v_add_f32_e32 v69, v69, v246
	v_lshlrev_b32_e32 v250, 16, v247
	v_and_b32_e32 v247, 0xffff0000, v247
	v_add_f32_e32 v70, v70, v250
	v_add_f32_e32 v71, v71, v247
	v_lshlrev_b32_e32 v250, 16, v248
	v_and_b32_e32 v248, 0xffff0000, v248
	v_add_f32_e32 v64, v64, v250
	v_add_f32_e32 v65, v65, v248
	v_lshlrev_b32_e32 v250, 16, v249
	v_and_b32_e32 v249, 0xffff0000, v249
	v_add_f32_e32 v66, v66, v250
	v_add_f32_e32 v67, v67, v249
	s_branch .Lmy_rb_done
.Lmy_rb_4:
	v_lshlrev_b32_e32 v250, 16, v242
	v_and_b32_e32 v242, 0xffff0000, v242
	v_add_f32_e32 v60, v60, v250
	v_add_f32_e32 v61, v61, v242
	v_lshlrev_b32_e32 v250, 16, v243
	v_and_b32_e32 v243, 0xffff0000, v243
	v_add_f32_e32 v62, v62, v250
	v_add_f32_e32 v63, v63, v243
	v_lshlrev_b32_e32 v250, 16, v244
	v_and_b32_e32 v244, 0xffff0000, v244
	v_add_f32_e32 v56, v56, v250
	v_add_f32_e32 v57, v57, v244
	v_lshlrev_b32_e32 v250, 16, v245
	v_and_b32_e32 v245, 0xffff0000, v245
	v_add_f32_e32 v58, v58, v250
	v_add_f32_e32 v59, v59, v245
	v_lshlrev_b32_e32 v250, 16, v246
	v_and_b32_e32 v246, 0xffff0000, v246
	v_add_f32_e32 v48, v48, v250
	v_add_f32_e32 v49, v49, v246
	v_lshlrev_b32_e32 v250, 16, v247
	v_and_b32_e32 v247, 0xffff0000, v247
	v_add_f32_e32 v50, v50, v250
	v_add_f32_e32 v51, v51, v247
	v_lshlrev_b32_e32 v250, 16, v248
	v_and_b32_e32 v248, 0xffff0000, v248
	v_add_f32_e32 v44, v44, v250
	v_add_f32_e32 v45, v45, v248
	v_lshlrev_b32_e32 v250, 16, v249
	v_and_b32_e32 v249, 0xffff0000, v249
	v_add_f32_e32 v46, v46, v250
	v_add_f32_e32 v47, v47, v249
	s_branch .Lmy_rb_done
.Lmy_rb_5:
	v_lshlrev_b32_e32 v250, 16, v242
	v_and_b32_e32 v242, 0xffff0000, v242
	v_add_f32_e32 v52, v52, v250
	v_add_f32_e32 v53, v53, v242
	v_lshlrev_b32_e32 v250, 16, v243
	v_and_b32_e32 v243, 0xffff0000, v243
	v_add_f32_e32 v54, v54, v250
	v_add_f32_e32 v55, v55, v243
	v_lshlrev_b32_e32 v250, 16, v244
	v_and_b32_e32 v244, 0xffff0000, v244
	v_add_f32_e32 v40, v40, v250
	v_add_f32_e32 v41, v41, v244
	v_lshlrev_b32_e32 v250, 16, v245
	v_and_b32_e32 v245, 0xffff0000, v245
	v_add_f32_e32 v42, v42, v250
	v_add_f32_e32 v43, v43, v245
	v_lshlrev_b32_e32 v250, 16, v246
	v_and_b32_e32 v246, 0xffff0000, v246
	v_add_f32_e32 v32, v32, v250
	v_add_f32_e32 v33, v33, v246
	v_lshlrev_b32_e32 v250, 16, v247
	v_and_b32_e32 v247, 0xffff0000, v247
	v_add_f32_e32 v34, v34, v250
	v_add_f32_e32 v35, v35, v247
	v_lshlrev_b32_e32 v250, 16, v248
	v_and_b32_e32 v248, 0xffff0000, v248
	v_add_f32_e32 v28, v28, v250
	v_add_f32_e32 v29, v29, v248
	v_lshlrev_b32_e32 v250, 16, v249
	v_and_b32_e32 v249, 0xffff0000, v249
	v_add_f32_e32 v30, v30, v250
	v_add_f32_e32 v31, v31, v249
	s_branch .Lmy_rb_done
; __device__ __forceinline__ u32x4 pack8(const f32x4 a, const f32x4 b) { u32x4 w; w.x = cvt_pk_bf16(a[0], a[1]); w.y = cvt_pk_bf16(a[2], a[3]); w.z = cvt_pk_bf16(b[0], b[1]); w.w = cvt_pk_bf16(b[2], b[3]); return w; }
; __device__ __forceinline__ void unpack8(const u32x4 w, f32x4& a, f32x4& b) { a = (f32x4){bflo(w.x), bfhi(w.x), bflo(w.y), bfhi(w.y)}; b = (f32x4){bflo(w.z), bfhi(w.z), bflo(w.w), bfhi(w.w)}; }
; #define PG8_STAGE(bufoff, gbase, voff) do { _Pragma("unroll") for (int _i = 0; _i < 2; ++_i) \
;         __builtin_amdgcn_global_load_lds((const unsigned*)((const char*)(gbase) + (voff)[_i]), (PG8_LAS unsigned*)(lds + (bufoff) + ldsw + _i * 8192), 16, 0, 0); } while (0)
; #define PG8_LDA(dst, b, h) do { _Pragma("unroll") for (int m = 0; m < 4; ++m) _Pragma("unroll") for (int k = 0; k < 2; ++k) dst[m][k] = *(const PG8_LAS bf16x8*)(lds + PG8_SA(b, h) + aoff + m * 2048 + k * 1024); } while (0)
; #define PG8_BAR __builtin_amdgcn_s_barrier()
;     __device__ __forceinline__ void operator()(const f32x4 (&acc)[2][2][4][2], const Unit& u, int wr, int wc, int fr, int fq) const {
;     ...
;             for (int m = 0; m < 4; ++m) { const size_t off = (size_t)(row0 + ai * HALF + m * 16) * 1024 + col0;
; #pragma unroll
;                 for (int bj = 0; bj < 2; ++bj) { f32x4 b0, b1;
;                     if (BF) { unpack8(*(const u32x4*)((const bf16_t*)base + off + bj * HALF), b0, b1); }
;                     else { b0 = *(const f32x4*)((const float*)base + off + bj * HALF); b1 = *(const f32x4*)((const float*)base + off + bj * HALF + 4); }
;                     *(u32x4*)(O + off + bj * HALF) = pack8(b0 + acc[ai][bj][m][0], b1 + acc[ai][bj][m][1]); } }
; template <class Epi, class Sched, bool ALIGN_EPI = false, bool SP2 = false>
; __device__ __forceinline__ void gemm_phase(PG8_LAS unsigned char* lds, const Gemm g, const Sched& S, const Epi& E, const int tid_in) {
;     ...
;             PG8_LDB(B0, 0, 0); PG8_LDB(B1, 0, 1); PG8_SCHED; PG8_LDA(At, 0, 0); PG8_STAGE(PG8_SA(1, 1), a1 + hstep, voffA);
;             PG8_WAIT_V(8); PG8_WAIT_L(0); PG8_BAR; PG8_MMA(0, 0, At, B0); PG8_MMA(0, 1, At, B1); PG8_BAR; PG8_SCHED;
;             PG8_LDA(At, 0, 1); PG8_STAGE(PG8_SB(0, 0), b2, voffB); PG8_STAGE(PG8_SB(0, 1), b2 + hstep, voffB); PG8_STAGE(PG8_SA(0, 0), a2, voffA);
;             PG8_WAIT_V(8); PG8_WAIT_L(0); PG8_BAR; PG8_MMA(1, 0, At, B0); PG8_MMA(1, 1, At, B1); PG8_BAR; PG8_SCHED;
.Lmy_rb_6:
	v_lshlrev_b32_e32 v250, 16, v242
	v_and_b32_e32 v242, 0xffff0000, v242
	v_add_f32_e32 v36, v36, v250
	v_add_f32_e32 v37, v37, v242
	v_lshlrev_b32_e32 v250, 16, v243
	v_and_b32_e32 v243, 0xffff0000, v243
	v_add_f32_e32 v38, v38, v250
	v_add_f32_e32 v39, v39, v243
	v_lshlrev_b32_e32 v250, 16, v244
	v_and_b32_e32 v244, 0xffff0000, v244
	v_add_f32_e32 v24, v24, v250
	v_add_f32_e32 v25, v25, v244
	v_lshlrev_b32_e32 v250, 16, v245
	v_and_b32_e32 v245, 0xffff0000, v245
	v_add_f32_e32 v26, v26, v250
	v_add_f32_e32 v27, v27, v245
	v_lshlrev_b32_e32 v250, 16, v246
	v_and_b32_e32 v246, 0xffff0000, v246
	v_add_f32_e32 v16, v16, v250
	v_add_f32_e32 v17, v17, v246
	v_lshlrev_b32_e32 v250, 16, v247
	v_and_b32_e32 v247, 0xffff0000, v247
	v_add_f32_e32 v18, v18, v250
	v_add_f32_e32 v19, v19, v247
	v_lshlrev_b32_e32 v250, 16, v248
	v_and_b32_e32 v248, 0xffff0000, v248
	v_add_f32_e32 v12, v12, v250
	v_add_f32_e32 v13, v13, v248
	v_lshlrev_b32_e32 v250, 16, v249
	v_and_b32_e32 v249, 0xffff0000, v249
	v_add_f32_e32 v14, v14, v250
	v_add_f32_e32 v15, v15, v249
.Lmy_rb_done:
	s_barrier
	s_setprio 1
	s_waitcnt lgkmcnt(0)
	v_mfma_f32_16x16x32_bf16 v[124:127], v[144:147], v[200:203], v[124:127]
	v_mfma_f32_16x16x32_bf16 v[120:123], v[176:179], v[200:203], v[120:123]
	v_mfma_f32_16x16x32_bf16 v[116:119], v[144:147], v[208:211], v[116:119]
	v_mfma_f32_16x16x32_bf16 v[104:107], v[176:179], v[208:211], v[104:107]
	v_mfma_f32_16x16x32_bf16 v[100:103], v[144:147], v[216:219], v[100:103]
	v_mfma_f32_16x16x32_bf16 v[88:91], v[176:179], v[216:219], v[88:91]
	v_mfma_f32_16x16x32_bf16 v[84:87], v[144:147], v[224:227], v[84:87]
	v_mfma_f32_16x16x32_bf16 v[72:75], v[176:179], v[224:227], v[72:75]
	v_mfma_f32_16x16x32_bf16 v[124:127], v[172:175], v[204:207], v[124:127]
	v_mfma_f32_16x16x32_bf16 v[120:123], v[180:183], v[204:207], v[120:123]
	v_mfma_f32_16x16x32_bf16 v[116:119], v[172:175], v[212:215], v[116:119]
	v_mfma_f32_16x16x32_bf16 v[104:107], v[180:183], v[212:215], v[104:107]
	v_mfma_f32_16x16x32_bf16 v[100:103], v[172:175], v[220:223], v[100:103]
	v_mfma_f32_16x16x32_bf16 v[88:91], v[180:183], v[220:223], v[88:91]
	v_mfma_f32_16x16x32_bf16 v[84:87], v[172:175], v[228:231], v[84:87]
	v_mfma_f32_16x16x32_bf16 v[72:75], v[180:183], v[228:231], v[72:75]
	s_setprio 0
	s_setprio 1
	v_mfma_f32_16x16x32_bf16 v[112:115], v[184:187], v[200:203], v[112:115]
	v_mfma_f32_16x16x32_bf16 v[108:111], v[192:195], v[200:203], v[108:111]
	v_mfma_f32_16x16x32_bf16 v[96:99], v[184:187], v[208:211], v[96:99]
	v_mfma_f32_16x16x32_bf16 v[92:95], v[192:195], v[208:211], v[92:95]
	v_mfma_f32_16x16x32_bf16 v[80:83], v[184:187], v[216:219], v[80:83]
	v_mfma_f32_16x16x32_bf16 v[76:79], v[192:195], v[216:219], v[76:79]
	v_mfma_f32_16x16x32_bf16 v[68:71], v[184:187], v[224:227], v[68:71]
	v_mfma_f32_16x16x32_bf16 v[64:67], v[192:195], v[224:227], v[64:67]
	v_mfma_f32_16x16x32_bf16 v[112:115], v[188:191], v[204:207], v[112:115]
	v_mfma_f32_16x16x32_bf16 v[108:111], v[196:199], v[204:207], v[108:111]
	v_mfma_f32_16x16x32_bf16 v[96:99], v[188:191], v[212:215], v[96:99]
	v_mfma_f32_16x16x32_bf16 v[92:95], v[196:199], v[212:215], v[92:95]
	v_mfma_f32_16x16x32_bf16 v[80:83], v[188:191], v[220:223], v[80:83]
	v_mfma_f32_16x16x32_bf16 v[76:79], v[196:199], v[220:223], v[76:79]
	v_mfma_f32_16x16x32_bf16 v[68:71], v[188:191], v[228:231], v[68:71]
	v_mfma_f32_16x16x32_bf16 v[64:67], v[196:199], v[228:231], v[64:67]
	s_setprio 0
	s_barrier
	s_add_i32 s71, s63, s56
	v_lshl_add_u64 v[148:149], s[42:43], 0, v[132:133]
	s_mov_b32 m0, s71
	ds_read_b128 v[200:203], v170 offset:16384
	ds_read_b128 v[204:207], v170 offset:17408
	ds_read_b128 v[208:211], v170 offset:18432
	ds_read_b128 v[212:215], v170 offset:19456
	ds_read_b128 v[216:219], v170 offset:20480
	ds_read_b128 v[220:223], v170 offset:21504
	ds_read_b128 v[224:227], v170 offset:22528
	ds_read_b128 v[228:231], v170 offset:23552
	global_load_lds_dwordx4 v[148:149], off
	s_add_i32 m0, s71, 0x2000
	s_add_u32 s72, s42, 0x40000
	v_lshl_add_u64 v[232:233], s[42:43], 0, v[128:129]
	s_addc_u32 s73, s43, 0
	s_add_i32 s71, s64, s56
	global_load_lds_dwordx4 v[232:233], off
	v_lshl_add_u64 v[234:235], s[72:73], 0, v[132:133]
	s_mov_b32 m0, s71
	v_lshl_add_u64 v[236:237], s[44:45], 0, v[130:131]
	global_load_lds_dwordx4 v[234:235], off
	v_lshl_add_u64 v[234:235], s[72:73], 0, v[128:129]
	s_add_i32 m0, s71, 0x2000
	s_nop 0
	global_load_lds_dwordx4 v[234:235], off
	v_lshl_add_u64 v[234:235], s[44:45], 0, v[134:135]
	s_mov_b32 m0, s41
	s_nop 0
	global_load_lds_dwordx4 v[234:235], off
	s_mov_b32 m0, s57
	s_nop 0
	global_load_lds_dwordx4 v[236:237], off
	s_waitcnt vmcnt(8)
	s_waitcnt lgkmcnt(0)
	global_load_dwordx4 v[242:245], v[240:241], off
	global_load_dwordx4 v[246:249], v[240:241], off offset:256
	s_mov_b32 s98, 0x8000
	s_cmp_eq_u32 s70, 4
	s_cselect_b32 s98, 0x28000, s98
	v_add_co_u32_e32 v240, vcc, s98, v240
	s_nop 1
	v_addc_co_u32_e32 v241, vcc, 0, v241, vcc
	s_barrier
; #define PG8_STAGE(bufoff, gbase, voff) do { _Pragma("unroll") for (int _i = 0; _i < 2; ++_i) \
;         __builtin_amdgcn_global_load_lds((const unsigned*)((const char*)(gbase) + (voff)[_i]), (PG8_LAS unsigned*)(lds + (bufoff) + ldsw + _i * 8192), 16, 0, 0); } while (0)
; #define PG8_LDA(dst, b, h) do { _Pragma("unroll") for (int m = 0; m < 4; ++m) _Pragma("unroll") for (int k = 0; k < 2; ++k) dst[m][k] = *(const PG8_LAS bf16x8*)(lds + PG8_SA(b, h) + aoff + m * 2048 + k * 1024); } while (0)
; #define PG8_LDB(dst, b, h) do { _Pragma("unroll") for (int n = 0; n < 2; ++n) _Pragma("unroll") for (int k = 0; k < 2; ++k) dst[n][k] = *(const PG8_LAS bf16x8*)(lds + PG8_SB(b, h) + boff + n * 2048 + k * 1024); } while (0)
; #define PG8_MMA(ai, bj, At, Bt) do { __builtin_amdgcn_s_setprio(1); _Pragma("unroll") for (int m = 0; m < 4; ++m) _Pragma("unroll") for (int n = 0; n < 2; ++n) _Pragma("unroll") for (int k = 0; k < 2; ++k) \
;         acc[ai][bj][m][n] = __builtin_amdgcn_mfma_f32_16x16x32_bf16(Bt[n][k], At[m][k], acc[ai][bj][m][n], 0, 0, 0); __builtin_amdgcn_s_setprio(0); } while (0)
; #define PG8_WAIT_V(n) asm volatile("s_waitcnt vmcnt(" #n ")" ::: "memory")
; #define PG8_WAIT_L(n) asm volatile("s_waitcnt lgkmcnt(" #n ")" ::: "memory")
; #define PG8_BAR __builtin_amdgcn_s_barrier()
; #define PG8_SCHED __builtin_amdgcn_sched_barrier(0)
; template <class Epi, class Sched, bool ALIGN_EPI = false, bool SP2 = false>
; __device__ __forceinline__ void gemm_phase(PG8_LAS unsigned char* lds, const Gemm g, const Sched& S, const Epi& E, const int tid_in) {
;     ...
;             PG8_WAIT_V(8); PG8_WAIT_L(0); PG8_BAR; PG8_MMA(1, 0, At, B0); PG8_MMA(1, 1, At, B1); PG8_BAR; PG8_SCHED;
;             PG8_LDB(B0, 1, 0); PG8_LDB(B1, 1, 1); PG8_SCHED; PG8_LDA(At, 1, 0); PG8_STAGE(PG8_SA(0, 1), a2 + hstep, voffA);
;             PG8_WAIT_V(8); PG8_WAIT_L(0); PG8_BAR; PG8_MMA(0, 0, At, B0); PG8_MMA(0, 1, At, B1); PG8_BAR; PG8_SCHED;
	s_setprio 1
	s_waitcnt lgkmcnt(0)
	v_mfma_f32_16x16x32_bf16 v[60:63], v[144:147], v[200:203], v[60:63]
	v_mfma_f32_16x16x32_bf16 v[56:59], v[176:179], v[200:203], v[56:59]
	v_mfma_f32_16x16x32_bf16 v[52:55], v[144:147], v[208:211], v[52:55]
	v_mfma_f32_16x16x32_bf16 v[40:43], v[176:179], v[208:211], v[40:43]
	v_mfma_f32_16x16x32_bf16 v[36:39], v[144:147], v[216:219], v[36:39]
	v_mfma_f32_16x16x32_bf16 v[24:27], v[176:179], v[216:219], v[24:27]
	v_mfma_f32_16x16x32_bf16 v[20:23], v[144:147], v[224:227], v[20:23]
	v_mfma_f32_16x16x32_bf16 v[8:11], v[176:179], v[224:227], v[8:11]
	v_mfma_f32_16x16x32_bf16 v[60:63], v[172:175], v[204:207], v[60:63]
	v_mfma_f32_16x16x32_bf16 v[56:59], v[180:183], v[204:207], v[56:59]
	v_mfma_f32_16x16x32_bf16 v[52:55], v[172:175], v[212:215], v[52:55]
	v_mfma_f32_16x16x32_bf16 v[40:43], v[180:183], v[212:215], v[40:43]
	v_mfma_f32_16x16x32_bf16 v[36:39], v[172:175], v[220:223], v[36:39]
	v_mfma_f32_16x16x32_bf16 v[24:27], v[180:183], v[220:223], v[24:27]
	v_mfma_f32_16x16x32_bf16 v[20:23], v[172:175], v[228:231], v[20:23]
	v_mfma_f32_16x16x32_bf16 v[8:11], v[180:183], v[228:231], v[8:11]
	s_setprio 0
	s_setprio 1
	v_mfma_f32_16x16x32_bf16 v[48:51], v[184:187], v[200:203], v[48:51]
	v_mfma_f32_16x16x32_bf16 v[44:47], v[192:195], v[200:203], v[44:47]
	v_mfma_f32_16x16x32_bf16 v[32:35], v[184:187], v[208:211], v[32:35]
	v_mfma_f32_16x16x32_bf16 v[28:31], v[192:195], v[208:211], v[28:31]
	v_mfma_f32_16x16x32_bf16 v[16:19], v[184:187], v[216:219], v[16:19]
	v_mfma_f32_16x16x32_bf16 v[12:15], v[192:195], v[216:219], v[12:15]
	v_mfma_f32_16x16x32_bf16 v[4:7], v[184:187], v[224:227], v[4:7]
	v_mfma_f32_16x16x32_bf16 v[0:3], v[192:195], v[224:227], v[0:3]
	v_mfma_f32_16x16x32_bf16 v[48:51], v[188:191], v[204:207], v[48:51]
	v_mfma_f32_16x16x32_bf16 v[44:47], v[196:199], v[204:207], v[44:47]
	v_mfma_f32_16x16x32_bf16 v[32:35], v[188:191], v[212:215], v[32:35]
	v_mfma_f32_16x16x32_bf16 v[28:31], v[196:199], v[212:215], v[28:31]
	v_mfma_f32_16x16x32_bf16 v[16:19], v[188:191], v[220:223], v[16:19]
	v_mfma_f32_16x16x32_bf16 v[12:15], v[196:199], v[220:223], v[12:15]
	v_mfma_f32_16x16x32_bf16 v[4:7], v[188:191], v[228:231], v[4:7]
	v_mfma_f32_16x16x32_bf16 v[0:3], v[196:199], v[228:231], v[0:3]
	s_setprio 0
	s_barrier
	s_add_i32 s71, 0, 0x18000
	v_add_u32_e32 v171, s71, v166
	s_add_i32 s72, 0, 0x1c000
	ds_read_b128 v[144:147], v171
	ds_read_b128 v[172:175], v171 offset:1024
	ds_read_b128 v[176:179], v171 offset:2048
	ds_read_b128 v[180:183], v171 offset:3072
	v_add_u32_e32 v171, s72, v166
	ds_read_b128 v[184:187], v171
	ds_read_b128 v[188:191], v171 offset:1024
	ds_read_b128 v[192:195], v171 offset:2048
	ds_read_b128 v[196:199], v171 offset:3072
	s_add_u32 s44, s44, 0x40000
	s_addc_u32 s45, s45, 0
	s_mov_b32 m0, s58
	v_lshl_add_u64 v[238:239], s[44:45], 0, v[134:135]
	ds_read_b128 v[200:203], v170 offset:32768
	ds_read_b128 v[204:207], v170 offset:33792
	ds_read_b128 v[208:211], v170 offset:34816
	ds_read_b128 v[212:215], v170 offset:35840
	ds_read_b128 v[216:219], v170 offset:36864
	ds_read_b128 v[220:223], v170 offset:37888
	ds_read_b128 v[224:227], v170 offset:38912
	ds_read_b128 v[228:231], v170 offset:39936
	global_load_lds_dwordx4 v[238:239], off
	v_lshl_add_u64 v[238:239], s[44:45], 0, v[130:131]
	s_mov_b32 m0, s59
	s_nop 0
	global_load_lds_dwordx4 v[238:239], off
	s_waitcnt vmcnt(10)
	s_waitcnt lgkmcnt(0)
	s_barrier
	s_setprio 1
	s_waitcnt lgkmcnt(0)
	v_mfma_f32_16x16x32_bf16 v[124:127], v[144:147], v[200:203], v[124:127]
	v_mfma_f32_16x16x32_bf16 v[120:123], v[176:179], v[200:203], v[120:123]
	v_mfma_f32_16x16x32_bf16 v[116:119], v[144:147], v[208:211], v[116:119]
	v_mfma_f32_16x16x32_bf16 v[104:107], v[176:179], v[208:211], v[104:107]
	v_mfma_f32_16x16x32_bf16 v[100:103], v[144:147], v[216:219], v[100:103]
	v_mfma_f32_16x16x32_bf16 v[88:91], v[176:179], v[216:219], v[88:91]
	v_mfma_f32_16x16x32_bf16 v[84:87], v[144:147], v[224:227], v[84:87]
	v_mfma_f32_16x16x32_bf16 v[72:75], v[176:179], v[224:227], v[72:75]
	v_mfma_f32_16x16x32_bf16 v[124:127], v[172:175], v[204:207], v[124:127]
	v_mfma_f32_16x16x32_bf16 v[120:123], v[180:183], v[204:207], v[120:123]
	v_mfma_f32_16x16x32_bf16 v[116:119], v[172:175], v[212:215], v[116:119]
	v_mfma_f32_16x16x32_bf16 v[104:107], v[180:183], v[212:215], v[104:107]
	v_mfma_f32_16x16x32_bf16 v[100:103], v[172:175], v[220:223], v[100:103]
	v_mfma_f32_16x16x32_bf16 v[88:91], v[180:183], v[220:223], v[88:91]
	v_mfma_f32_16x16x32_bf16 v[84:87], v[172:175], v[228:231], v[84:87]
	v_mfma_f32_16x16x32_bf16 v[72:75], v[180:183], v[228:231], v[72:75]
	s_setprio 0
	s_setprio 1
	v_mfma_f32_16x16x32_bf16 v[112:115], v[184:187], v[200:203], v[112:115]
	v_mfma_f32_16x16x32_bf16 v[108:111], v[192:195], v[200:203], v[108:111]
	v_mfma_f32_16x16x32_bf16 v[96:99], v[184:187], v[208:211], v[96:99]
	v_mfma_f32_16x16x32_bf16 v[92:95], v[192:195], v[208:211], v[92:95]
	v_mfma_f32_16x16x32_bf16 v[80:83], v[184:187], v[216:219], v[80:83]
	v_mfma_f32_16x16x32_bf16 v[76:79], v[192:195], v[216:219], v[76:79]
	v_mfma_f32_16x16x32_bf16 v[68:71], v[184:187], v[224:227], v[68:71]
	v_mfma_f32_16x16x32_bf16 v[64:67], v[192:195], v[224:227], v[64:67]
	v_mfma_f32_16x16x32_bf16 v[112:115], v[188:191], v[204:207], v[112:115]
	v_mfma_f32_16x16x32_bf16 v[108:111], v[196:199], v[204:207], v[108:111]
	v_mfma_f32_16x16x32_bf16 v[96:99], v[188:191], v[212:215], v[96:99]
	v_mfma_f32_16x16x32_bf16 v[92:95], v[196:199], v[212:215], v[92:95]
	v_mfma_f32_16x16x32_bf16 v[80:83], v[188:191], v[220:223], v[80:83]
	v_mfma_f32_16x16x32_bf16 v[76:79], v[196:199], v[220:223], v[76:79]
	v_mfma_f32_16x16x32_bf16 v[68:71], v[188:191], v[228:231], v[68:71]
	v_mfma_f32_16x16x32_bf16 v[64:67], v[196:199], v[228:231], v[64:67]
	s_setprio 0
	s_barrier
; #define PG8_STAGE(bufoff, gbase, voff) do { _Pragma("unroll") for (int _i = 0; _i < 2; ++_i) \
;         __builtin_amdgcn_global_load_lds((const unsigned*)((const char*)(gbase) + (voff)[_i]), (PG8_LAS unsigned*)(lds + (bufoff) + ldsw + _i * 8192), 16, 0, 0); } while (0)
; #define PG8_LDA(dst, b, h) do { _Pragma("unroll") for (int m = 0; m < 4; ++m) _Pragma("unroll") for (int k = 0; k < 2; ++k) dst[m][k] = *(const PG8_LAS bf16x8*)(lds + PG8_SA(b, h) + aoff + m * 2048 + k * 1024); } while (0)
; #define PG8_MMA(ai, bj, At, Bt) do { __builtin_amdgcn_s_setprio(1); _Pragma("unroll") for (int m = 0; m < 4; ++m) _Pragma("unroll") for (int n = 0; n < 2; ++n) _Pragma("unroll") for (int k = 0; k < 2; ++k) \
;         acc[ai][bj][m][n] = __builtin_amdgcn_mfma_f32_16x16x32_bf16(Bt[n][k], At[m][k], acc[ai][bj][m][n], 0, 0, 0); __builtin_amdgcn_s_setprio(0); } while (0)
; #define PG8_WAIT_V(n) asm volatile("s_waitcnt vmcnt(" #n ")" ::: "memory")
; #define PG8_WAIT_L(n) asm volatile("s_waitcnt lgkmcnt(" #n ")" ::: "memory")
; #define PG8_BAR __builtin_amdgcn_s_barrier()
; #define PG8_SCHED __builtin_amdgcn_sched_barrier(0)
; template <class Epi, class Sched, bool ALIGN_EPI = false, bool SP2 = false>
; __device__ __forceinline__ void gemm_phase(PG8_LAS unsigned char* lds, const Gemm g, const Sched& S, const Epi& E, const int tid_in) {
;     ...
;             PG8_WAIT_V(8); PG8_WAIT_L(0); PG8_BAR; PG8_MMA(0, 0, At, B0); PG8_MMA(0, 1, At, B1); PG8_BAR; PG8_SCHED;
;             PG8_LDA(At, 1, 1); PG8_STAGE(PG8_SB(1, 0), b3, voffB); PG8_STAGE(PG8_SB(1, 1), b3 + hstep, voffB); PG8_STAGE(PG8_SA(1, 0), a3, voffA);
;             PG8_WAIT_V(8); PG8_WAIT_L(0); PG8_BAR; PG8_MMA(1, 0, At, B0); PG8_MMA(1, 1, At, B1); PG8_BAR; PG8_SCHED;
	s_add_i32 s44, s71, s56
	v_lshl_add_u64 v[148:149], v[148:149], 0, s[20:21]
	s_mov_b32 m0, s44
	ds_read_b128 v[200:203], v170 offset:49152
	ds_read_b128 v[204:207], v170 offset:50176
	ds_read_b128 v[208:211], v170 offset:51200
	ds_read_b128 v[212:215], v170 offset:52224
	ds_read_b128 v[216:219], v170 offset:53248
	ds_read_b128 v[220:223], v170 offset:54272
	ds_read_b128 v[224:227], v170 offset:55296
	ds_read_b128 v[228:231], v170 offset:56320
	global_load_lds_dwordx4 v[148:149], off
	s_add_i32 m0, s44, 0x2000
	s_add_u32 s42, s42, 0x40080
	v_lshl_add_u64 v[148:149], v[232:233], 0, s[20:21]
	s_addc_u32 s43, s43, 0
	s_add_i32 s44, s72, s56
	global_load_lds_dwordx4 v[148:149], off
	v_lshl_add_u64 v[148:149], s[42:43], 0, v[132:133]
	s_mov_b32 m0, s44
	s_nop 0
	global_load_lds_dwordx4 v[148:149], off
	v_lshl_add_u64 v[148:149], s[42:43], 0, v[128:129]
	s_add_i32 m0, s44, 0x2000
	s_nop 0
	global_load_lds_dwordx4 v[148:149], off
	v_lshl_add_u64 v[148:149], v[234:235], 0, s[20:21]
	s_mov_b32 m0, s60
	s_nop 0
	global_load_lds_dwordx4 v[148:149], off
	v_lshl_add_u64 v[148:149], v[236:237], 0, s[20:21]
	s_mov_b32 m0, s61
	s_nop 0
	global_load_lds_dwordx4 v[148:149], off
	s_waitcnt vmcnt(10)
	s_waitcnt lgkmcnt(0)
	s_barrier
	s_setprio 1
	s_waitcnt lgkmcnt(0)
	v_mfma_f32_16x16x32_bf16 v[60:63], v[144:147], v[200:203], v[60:63]
	v_mfma_f32_16x16x32_bf16 v[56:59], v[176:179], v[200:203], v[56:59]
	v_mfma_f32_16x16x32_bf16 v[52:55], v[144:147], v[208:211], v[52:55]
	v_mfma_f32_16x16x32_bf16 v[40:43], v[176:179], v[208:211], v[40:43]
	v_mfma_f32_16x16x32_bf16 v[36:39], v[144:147], v[216:219], v[36:39]
	v_mfma_f32_16x16x32_bf16 v[24:27], v[176:179], v[216:219], v[24:27]
	v_mfma_f32_16x16x32_bf16 v[20:23], v[144:147], v[224:227], v[20:23]
	v_mfma_f32_16x16x32_bf16 v[8:11], v[176:179], v[224:227], v[8:11]
	v_mfma_f32_16x16x32_bf16 v[60:63], v[172:175], v[204:207], v[60:63]
	v_mfma_f32_16x16x32_bf16 v[56:59], v[180:183], v[204:207], v[56:59]
	v_mfma_f32_16x16x32_bf16 v[52:55], v[172:175], v[212:215], v[52:55]
	v_mfma_f32_16x16x32_bf16 v[40:43], v[180:183], v[212:215], v[40:43]
	v_mfma_f32_16x16x32_bf16 v[36:39], v[172:175], v[220:223], v[36:39]
	v_mfma_f32_16x16x32_bf16 v[24:27], v[180:183], v[220:223], v[24:27]
	v_mfma_f32_16x16x32_bf16 v[20:23], v[172:175], v[228:231], v[20:23]
	v_mfma_f32_16x16x32_bf16 v[8:11], v[180:183], v[228:231], v[8:11]
	s_setprio 0
	s_setprio 1
	v_mfma_f32_16x16x32_bf16 v[48:51], v[184:187], v[200:203], v[48:51]
	v_mfma_f32_16x16x32_bf16 v[44:47], v[192:195], v[200:203], v[44:47]
	v_mfma_f32_16x16x32_bf16 v[32:35], v[184:187], v[208:211], v[32:35]
	v_mfma_f32_16x16x32_bf16 v[28:31], v[192:195], v[208:211], v[28:31]
	v_mfma_f32_16x16x32_bf16 v[16:19], v[184:187], v[216:219], v[16:19]
	v_mfma_f32_16x16x32_bf16 v[12:15], v[192:195], v[216:219], v[12:15]
	v_mfma_f32_16x16x32_bf16 v[4:7], v[184:187], v[224:227], v[4:7]
	v_mfma_f32_16x16x32_bf16 v[0:3], v[192:195], v[224:227], v[0:3]
	v_mfma_f32_16x16x32_bf16 v[48:51], v[188:191], v[204:207], v[48:51]
	v_mfma_f32_16x16x32_bf16 v[44:47], v[196:199], v[204:207], v[44:47]
	v_mfma_f32_16x16x32_bf16 v[32:35], v[188:191], v[212:215], v[32:35]
	v_mfma_f32_16x16x32_bf16 v[28:31], v[196:199], v[212:215], v[28:31]
	v_mfma_f32_16x16x32_bf16 v[16:19], v[188:191], v[220:223], v[16:19]
	v_mfma_f32_16x16x32_bf16 v[12:15], v[196:199], v[220:223], v[12:15]
	v_mfma_f32_16x16x32_bf16 v[4:7], v[188:191], v[228:231], v[4:7]
	v_mfma_f32_16x16x32_bf16 v[0:3], v[196:199], v[228:231], v[0:3]
	s_setprio 0
	s_barrier
	s_add_i32 s70, s70, 2
	s_add_u32 s0, s0, 0x100
	s_addc_u32 s1, s1, 0
	s_add_u32 s68, s68, 0x100
	s_addc_u32 s69, s69, 0
	s_cmp_gt_u32 s70, 13
	s_cbranch_scc0 .LBB0_1080
	s_and_b64 vcc, exec, s[22:23]
	s_cbranch_vccz .LBB0_1083
	s_barrier
; __device__ __forceinline__ u32x4 pack8(const f32x4 a, const f32x4 b) { u32x4 w; w.x = cvt_pk_bf16(a[0], a[1]); w.y = cvt_pk_bf16(a[2], a[3]); w.z = cvt_pk_bf16(b[0], b[1]); w.w = cvt_pk_bf16(b[2], b[3]); return w; }
; __device__ __forceinline__ void unpack8(const u32x4 w, f32x4& a, f32x4& b) { a = (f32x4){bflo(w.x), bfhi(w.x), bflo(w.y), bfhi(w.y)}; b = (f32x4){bflo(w.z), bfhi(w.z), bflo(w.w), bfhi(w.w)}; }
;     __device__ __forceinline__ void operator()(const f32x4 (&acc)[2][2][4][2], const Unit& u, int wr, int wc, int fr, int fq) const {
;     ...
;             for (int m = 0; m < 4; ++m) { const size_t off = (size_t)(row0 + ai * HALF + m * 16) * 1024 + col0;
; #pragma unroll
;                 for (int bj = 0; bj < 2; ++bj) { f32x4 b0, b1;
;                     if (BF) { unpack8(*(const u32x4*)((const bf16_t*)base + off + bj * HALF), b0, b1); }
;                     else { b0 = *(const f32x4*)((const float*)base + off + bj * HALF); b1 = *(const f32x4*)((const float*)base + off + bj * HALF + 4); }
;                     *(u32x4*)(O + off + bj * HALF) = pack8(b0 + acc[ai][bj][m][0], b1 + acc[ai][bj][m][1]); } }
.LBB0_1083:
	v_lshl_add_u32 v148, s40, 8, v165
	v_lshl_or_b32 v146, s65, 8, v167
	v_ashrrev_i32_e32 v149, 31, v148
	v_ashrrev_i32_e32 v147, 31, v146
	v_lshlrev_b64 v[144:145], 10, v[148:149]
	v_lshl_add_u64 v[144:145], v[144:145], 0, v[146:147]
	v_lshlrev_b64 v[144:145], 1, v[144:145]
	v_lshl_add_u64 v[174:175], s[18:19], 0, v[144:145]
	s_mov_b64 s[0:1], -1
	v_mov_b32_e32 v236, 0x8000
	v_mov_b32_e32 v237, 0
	v_lshl_add_u64 v[176:177], v[236:237], 0, v[174:175]
	v_lshl_add_u64 v[178:179], v[236:237], 1, v[174:175]
	v_lshl_add_u64 v[180:181], v[236:237], 1, v[176:177]
	v_lshl_add_u64 v[182:183], v[236:237], 3, v[174:175]
	v_lshl_add_u64 v[184:185], v[236:237], 0, v[182:183]
	v_lshl_add_u64 v[186:187], v[236:237], 1, v[182:183]
	v_lshl_add_u64 v[188:189], v[236:237], 1, v[184:185]
	s_waitcnt vmcnt(0)
	v_lshlrev_b32_e32 v250, 16, v242
	v_and_b32_e32 v242, 0xffff0000, v242
	v_add_f32_e32 v20, v20, v250
	v_add_f32_e32 v21, v21, v242
	v_lshlrev_b32_e32 v250, 16, v243
	v_and_b32_e32 v243, 0xffff0000, v243
	v_add_f32_e32 v22, v22, v250
	v_add_f32_e32 v23, v23, v243
	v_lshlrev_b32_e32 v250, 16, v244
	v_and_b32_e32 v244, 0xffff0000, v244
	v_add_f32_e32 v8, v8, v250
	v_add_f32_e32 v9, v9, v244
	v_lshlrev_b32_e32 v250, 16, v245
	v_and_b32_e32 v245, 0xffff0000, v245
	v_add_f32_e32 v10, v10, v250
	v_add_f32_e32 v11, v11, v245
	v_lshlrev_b32_e32 v250, 16, v246
	v_and_b32_e32 v246, 0xffff0000, v246
	v_add_f32_e32 v4, v4, v250
	v_add_f32_e32 v5, v5, v246
	v_lshlrev_b32_e32 v250, 16, v247
	v_and_b32_e32 v247, 0xffff0000, v247
	v_add_f32_e32 v6, v6, v250
	v_add_f32_e32 v7, v7, v247
	v_lshlrev_b32_e32 v250, 16, v248
	v_and_b32_e32 v248, 0xffff0000, v248
	v_add_f32_e32 v0, v0, v250
	v_add_f32_e32 v1, v1, v248
	v_lshlrev_b32_e32 v250, 16, v249
	v_and_b32_e32 v249, 0xffff0000, v249
	v_add_f32_e32 v2, v2, v250
	v_add_f32_e32 v3, v3, v249
	v_cvt_pk_bf16_f32 v192, v124, v125
	v_cvt_pk_bf16_f32 v193, v126, v127
	v_cvt_pk_bf16_f32 v194, v120, v121
	v_cvt_pk_bf16_f32 v195, v122, v123
	global_store_dwordx4 v[174:175], v[192:195], off
	v_cvt_pk_bf16_f32 v196, v112, v113
	v_cvt_pk_bf16_f32 v197, v114, v115
	v_cvt_pk_bf16_f32 v198, v108, v109
	v_cvt_pk_bf16_f32 v199, v110, v111
	global_store_dwordx4 v[174:175], v[196:199], off offset:256
	v_cvt_pk_bf16_f32 v200, v116, v117
	v_cvt_pk_bf16_f32 v201, v118, v119
	v_cvt_pk_bf16_f32 v202, v104, v105
	v_cvt_pk_bf16_f32 v203, v106, v107
	global_store_dwordx4 v[176:177], v[200:203], off
	v_cvt_pk_bf16_f32 v204, v96, v97
	v_cvt_pk_bf16_f32 v205, v98, v99
	v_cvt_pk_bf16_f32 v206, v92, v93
	v_cvt_pk_bf16_f32 v207, v94, v95
	global_store_dwordx4 v[176:177], v[204:207], off offset:256
	v_cvt_pk_bf16_f32 v208, v100, v101
	v_cvt_pk_bf16_f32 v209, v102, v103
	v_cvt_pk_bf16_f32 v210, v88, v89
	v_cvt_pk_bf16_f32 v211, v90, v91
	global_store_dwordx4 v[178:179], v[208:211], off
	v_cvt_pk_bf16_f32 v212, v80, v81
	v_cvt_pk_bf16_f32 v213, v82, v83
	v_cvt_pk_bf16_f32 v214, v76, v77
	v_cvt_pk_bf16_f32 v215, v78, v79
	global_store_dwordx4 v[178:179], v[212:215], off offset:256
	v_cvt_pk_bf16_f32 v216, v84, v85
	v_cvt_pk_bf16_f32 v217, v86, v87
	v_cvt_pk_bf16_f32 v218, v72, v73
	v_cvt_pk_bf16_f32 v219, v74, v75
	global_store_dwordx4 v[180:181], v[216:219], off
	v_cvt_pk_bf16_f32 v220, v68, v69
	v_cvt_pk_bf16_f32 v221, v70, v71
	v_cvt_pk_bf16_f32 v222, v64, v65
	v_cvt_pk_bf16_f32 v223, v66, v67
	global_store_dwordx4 v[180:181], v[220:223], off offset:256
	v_cvt_pk_bf16_f32 v192, v60, v61
	v_cvt_pk_bf16_f32 v193, v62, v63
	v_cvt_pk_bf16_f32 v194, v56, v57
	v_cvt_pk_bf16_f32 v195, v58, v59
	global_store_dwordx4 v[182:183], v[192:195], off
	v_cvt_pk_bf16_f32 v196, v48, v49
	v_cvt_pk_bf16_f32 v197, v50, v51
	v_cvt_pk_bf16_f32 v198, v44, v45
	v_cvt_pk_bf16_f32 v199, v46, v47
	global_store_dwordx4 v[182:183], v[196:199], off offset:256
	v_cvt_pk_bf16_f32 v200, v52, v53
	v_cvt_pk_bf16_f32 v201, v54, v55
	v_cvt_pk_bf16_f32 v202, v40, v41
	v_cvt_pk_bf16_f32 v203, v42, v43
	global_store_dwordx4 v[184:185], v[200:203], off
	v_cvt_pk_bf16_f32 v204, v32, v33
	v_cvt_pk_bf16_f32 v205, v34, v35
	v_cvt_pk_bf16_f32 v206, v28, v29
	v_cvt_pk_bf16_f32 v207, v30, v31
	global_store_dwordx4 v[184:185], v[204:207], off offset:256
	v_cvt_pk_bf16_f32 v208, v36, v37
	v_cvt_pk_bf16_f32 v209, v38, v39
	v_cvt_pk_bf16_f32 v210, v24, v25
	v_cvt_pk_bf16_f32 v211, v26, v27
	global_store_dwordx4 v[186:187], v[208:211], off
	v_cvt_pk_bf16_f32 v212, v16, v17
	v_cvt_pk_bf16_f32 v213, v18, v19
	v_cvt_pk_bf16_f32 v214, v12, v13
	v_cvt_pk_bf16_f32 v215, v14, v15
	global_store_dwordx4 v[186:187], v[212:215], off offset:256
	v_cvt_pk_bf16_f32 v216, v20, v21
	v_cvt_pk_bf16_f32 v217, v22, v23
	v_cvt_pk_bf16_f32 v218, v8, v9
	v_cvt_pk_bf16_f32 v219, v10, v11
	global_store_dwordx4 v[188:189], v[216:219], off
	v_cvt_pk_bf16_f32 v220, v4, v5
	v_cvt_pk_bf16_f32 v221, v6, v7
	v_cvt_pk_bf16_f32 v222, v0, v1
	v_cvt_pk_bf16_f32 v223, v2, v3
	global_store_dwordx4 v[188:189], v[220:223], off offset:256
	s_andn2_b64 vcc, exec, s[2:3]
	s_cbranch_vccnz .LBB0_1072
	s_andn2_b64 vcc, exec, s[14:15]
	s_cbranch_vccnz .LBB0_1071
	s_barrier
	s_branch .LBB0_1071
